# grid barrier: non-leader workgroups spin on the cross-XCC generation word directly instead of waiting for their XCC leader's relay
# speedup vs baseline: 1.0088x; 1.0088x over previous
.LBB0_724:
	v_readlane_b32 s8, v254, 17
	v_readlane_b32 s9, v254, 18
	v_mov_b32_e32 v1, 1
	v_sub_u32_e32 v4, 0, v2
	s_nop 2
	global_atomic_add v3, v161, v1, s[8:9] sc0
	v_cvt_f32_u32_e32 v1, v2
	v_rcp_iflag_f32_e32 v1, v1
	s_nop 0
	v_mul_f32_e32 v1, 0x4f7ffffe, v1
	v_cvt_u32_f32_e32 v1, v1
	v_mul_lo_u32 v4, v4, v1
	v_mul_hi_u32 v4, v1, v4
	v_add_u32_e32 v1, v1, v4
	s_waitcnt vmcnt(0)
	v_mul_hi_u32 v1, v3, v1
	v_mul_lo_u32 v4, v1, v2
	v_sub_u32_e32 v4, v3, v4
	v_add_u32_e32 v5, 1, v1
	v_cmp_ge_u32_e32 vcc, v4, v2
	v_add_u32_e32 v3, 1, v3
	s_nop 0
	v_cndmask_b32_e32 v1, v1, v5, vcc
	v_sub_u32_e32 v5, v4, v2
	v_cndmask_b32_e32 v4, v4, v5, vcc
	v_add_u32_e32 v5, 1, v1
	v_cmp_ge_u32_e32 vcc, v4, v2
	s_nop 1
	v_cndmask_b32_e32 v1, v1, v5, vcc
	v_mul_lo_u32 v4, v2, v1
	v_add_u32_e32 v2, v4, v2
	v_cmp_ne_u32_e32 vcc, v3, v2
	s_and_saveexec_b64 s[8:9], vcc
	s_xor_b64 s[8:9], exec, s[8:9]
	s_cbranch_execz .LBB0_738
	v_readlane_b32 s10, v254, 23
	v_readlane_b32 s11, v254, 24
	s_waitcnt lgkmcnt(0)
	s_nop 3
	global_load_dword v0, v161, s[10:11] sc1
	s_waitcnt vmcnt(0)
	v_cmp_eq_u32_e32 vcc, v0, v1
	s_and_saveexec_b64 s[10:11], vcc
	s_cbranch_execz .LBB0_737
	s_mov_b32 s24, 1
	s_mov_b64 s[12:13], 0
	s_branch .LBB0_728

.LBB0_730:
	v_readlane_b32 s16, v254, 23
	v_readlane_b32 s17, v254, 24
	s_add_i32 s24, s24, 1
	s_mov_b64 s[18:19], -1
	s_nop 2
	global_load_dword v0, v161, s[16:17] sc1
	s_waitcnt vmcnt(0)
	v_cmp_ne_u32_e32 vcc, v0, v1
	s_orn2_b64 s[16:17], vcc, exec
	s_branch .LBB0_727
